# past sub-tile loop: softmax section with packed f32 subtract / row sums on (j,j+1) pairs, exps in place (26 fewer instructions per sub-tile)
# speedup vs baseline: 1.0101x; 1.0101x over previous
.LBB0_259:
	ds_read_b128 v[72:75], v116 offset:64
	ds_read_b128 v[100:103], v116 offset:2368
	v_mov_b32_e32 v163, v164
	v_add_u32_e32 v164, s0, v121
	s_waitcnt lgkmcnt(2)
	v_mfma_f32_16x16x32_bf16 v[198:201], v[234:237], v[40:43], 0
	v_mov_b32_e32 v165, v166
	v_add_u32_e32 v166, 0x2000, v164
	v_add_u32_e32 v167, 0x4000, v164
	v_mfma_f32_16x16x32_bf16 v[104:107], v[234:237], v[36:39], 0
	ds_read_b128 v[80:83], v116 offset:4608
	ds_read_b128 v[76:79], v116 offset:4672
	s_addk_i32 s0, 0x80
	s_cmpk_eq_i32 s0, 0x200
	v_mfma_f32_16x16x32_bf16 v[68:71], v[238:241], v[40:43], 0
	v_mfma_f32_16x16x32_bf16 v[64:67], v[238:241], v[36:39], 0
	s_waitcnt lgkmcnt(1)
	v_mfma_f32_16x16x32_bf16 v[92:95], v[80:83], v[40:43], 0
	v_mfma_f32_16x16x32_bf16 v[84:87], v[80:83], v[36:39], 0
	ds_read_b128 v[88:91], v116 offset:6912
	ds_read_b128 v[80:83], v116 offset:6976
	v_add_u32_e32 v116, 0x2400, v116
	s_waitcnt lgkmcnt(1)
	v_mfma_f32_16x16x32_bf16 v[96:99], v[88:91], v[40:43], 0
	v_mfma_f32_16x16x32_bf16 v[88:91], v[88:91], v[36:39], 0
	v_mfma_f32_16x16x32_bf16 v[68:71], v[72:75], v[44:47], v[68:71]
	v_mfma_f32_16x16x32_bf16 v[72:75], v[72:75], v[32:35], v[64:67]
	v_mfma_f32_16x16x32_bf16 v[64:67], v[100:103], v[44:47], v[198:201]
	v_mfma_f32_16x16x32_bf16 v[100:103], v[100:103], v[32:35], v[104:107]
	s_nop 2
	ds_read2_b64 v[104:107], v164 offset1:4
	ds_read2_b64 v[198:201], v164 offset0:8 offset1:12
	v_add_u32_e32 v164, 0x6000, v164
	v_mfma_f32_16x16x32_bf16 v[92:95], v[76:79], v[44:47], v[92:95]
	v_mfma_f32_16x16x32_bf16 v[76:79], v[76:79], v[32:35], v[84:87]
	s_nop 2
	ds_read2_b64 v[84:87], v166 offset0:32 offset1:36
	ds_read2_b64 v[202:205], v166 offset0:40 offset1:44
	ds_read2_b64 v[206:209], v167 offset0:64 offset1:68
	ds_read2_b64 v[210:213], v167 offset0:72 offset1:76
	ds_read2_b64 v[214:217], v164 offset0:96 offset1:100
	ds_read2_b64 v[218:221], v164 offset0:104 offset1:108
	s_waitcnt lgkmcnt(8)
	v_mfma_f32_16x16x32_bf16 v[96:99], v[80:83], v[44:47], v[96:99]
	v_mfma_f32_16x16x32_bf16 v[80:83], v[80:83], v[32:35], v[88:91]
	s_nop 2
	v_max3_f32 v88, v68, s4, v69
	v_max3_f32 v89, v72, s4, v73
	v_max3_f32 v88, v88, v70, v71
	v_max3_f32 v89, v89, v74, v75
	v_max3_f32 v88, v88, v64, v65
	v_max3_f32 v89, v89, v100, v101
	v_max3_f32 v88, v88, v66, v67
	v_max3_f32 v89, v89, v102, v103
	v_max3_f32 v88, v88, v92, v93
	v_max3_f32 v89, v89, v76, v77
	v_max3_f32 v88, v88, v94, v95
	v_max3_f32 v89, v89, v78, v79
	v_max3_f32 v88, v88, v96, v97
	v_max3_f32 v89, v89, v80, v81
	v_max3_f32 v88, v88, v98, v99
	v_max3_f32 v89, v89, v82, v83
	v_mov_b32_e32 v90, v88
	v_mov_b32_e32 v91, v89
	s_nop 0
	v_permlane16_swap_b32_e32 v90, v88
	v_permlane16_swap_b32_e32 v91, v89
	v_max_f32_e32 v88, v88, v90
	v_max_f32_e32 v89, v89, v91
	v_mov_b32_e32 v90, v88
	v_mov_b32_e32 v91, v89
	s_nop 0
	v_permlane32_swap_b32_e32 v90, v88
	v_permlane32_swap_b32_e32 v91, v89
	v_max3_f32 v164, v163, v89, v91
	v_max3_f32 v166, v165, v88, v90
	v_sub_f32_e32 v89, v163, v164
	v_sub_f32_e32 v88, v165, v166
	v_sub_f32_e32 v90, 0, v166
	v_sub_f32_e32 v178, 0, v164
	v_pk_add_f32 v[68:69], v[68:69], v[90:91] op_sel_hi:[1,0]
	v_pk_add_f32 v[70:71], v[70:71], v[90:91] op_sel_hi:[1,0]
	v_pk_add_f32 v[72:73], v[72:73], v[178:179] op_sel_hi:[1,0]
	v_pk_add_f32 v[74:75], v[74:75], v[178:179] op_sel_hi:[1,0]
	v_exp_f32_e32 v88, v88
	v_exp_f32_e32 v89, v89
	v_pk_add_f32 v[64:65], v[64:65], v[90:91] op_sel_hi:[1,0]
	v_pk_add_f32 v[66:67], v[66:67], v[90:91] op_sel_hi:[1,0]
	v_mov_b32_e32 v186, v89
	v_exp_f32_e32 v68, v68
	v_exp_f32_e32 v69, v69
	v_exp_f32_e32 v70, v70
	v_exp_f32_e32 v71, v71
	v_pk_add_f32 v[100:101], v[100:101], v[178:179] op_sel_hi:[1,0]
	v_pk_add_f32 v[102:103], v[102:103], v[178:179] op_sel_hi:[1,0]
	v_exp_f32_e32 v72, v72
	v_exp_f32_e32 v73, v73
	v_exp_f32_e32 v74, v74
	v_exp_f32_e32 v75, v75
	v_pk_mul_f32 v[60:61], v[60:61], v[88:89] op_sel_hi:[1,0]
	v_pk_mul_f32 v[62:63], v[62:63], v[88:89] op_sel_hi:[1,0]
	v_exp_f32_e32 v64, v64
	v_exp_f32_e32 v65, v65
	v_exp_f32_e32 v66, v66
	v_exp_f32_e32 v67, v67
	v_pk_mul_f32 v[56:57], v[56:57], v[88:89] op_sel_hi:[1,0]
	v_pk_mul_f32 v[58:59], v[58:59], v[88:89] op_sel_hi:[1,0]
	v_exp_f32_e32 v100, v100
	v_exp_f32_e32 v101, v101
	v_exp_f32_e32 v102, v102
	v_exp_f32_e32 v103, v103
	v_cvt_pk_bf16_f32 v222, v68, v69
	v_cvt_pk_bf16_f32 v223, v70, v71
	v_cvt_pk_bf16_f32 v224, v64, v65
	v_cvt_pk_bf16_f32 v225, v66, v67
	v_pk_mul_f32 v[28:29], v[28:29], v[186:187] op_sel_hi:[1,0]
	v_pk_mul_f32 v[30:31], v[30:31], v[186:187] op_sel_hi:[1,0]
	s_waitcnt lgkmcnt(7)
	v_mfma_f32_16x16x32_bf16 v[60:63], v[104:107], v[222:225], v[60:63]
	v_cvt_pk_bf16_f32 v226, v72, v73
	v_cvt_pk_bf16_f32 v227, v74, v75
	s_waitcnt lgkmcnt(5)
	v_mfma_f32_16x16x32_bf16 v[56:59], v[84:87], v[222:225], v[56:59]
	v_cvt_pk_bf16_f32 v228, v100, v101
	v_cvt_pk_bf16_f32 v229, v102, v103
	v_pk_mul_f32 v[24:25], v[24:25], v[186:187] op_sel_hi:[1,0]
	v_pk_mul_f32 v[26:27], v[26:27], v[186:187] op_sel_hi:[1,0]
	s_nop 1
	v_mfma_f32_16x16x32_bf16 v[28:31], v[104:107], v[226:229], v[28:31]
	v_pk_add_f32 v[92:93], v[92:93], v[90:91] op_sel_hi:[1,0]
	v_pk_add_f32 v[94:95], v[94:95], v[90:91] op_sel_hi:[1,0]
	v_pk_mul_f32 v[52:53], v[52:53], v[88:89] op_sel_hi:[1,0]
	v_pk_mul_f32 v[54:55], v[54:55], v[88:89] op_sel_hi:[1,0]
	v_mfma_f32_16x16x32_bf16 v[24:27], v[84:87], v[226:229], v[24:27]
	v_pk_add_f32 v[96:97], v[96:97], v[90:91] op_sel_hi:[1,0]
	v_pk_add_f32 v[98:99], v[98:99], v[90:91] op_sel_hi:[1,0]
	v_pk_mul_f32 v[48:49], v[48:49], v[88:89] op_sel_hi:[1,0]
	v_pk_mul_f32 v[50:51], v[50:51], v[88:89] op_sel_hi:[1,0]
	s_waitcnt lgkmcnt(3)
	v_mfma_f32_16x16x32_bf16 v[52:55], v[206:209], v[222:225], v[52:55]
	v_exp_f32_e32 v92, v92
	v_exp_f32_e32 v93, v93
	v_exp_f32_e32 v94, v94
	v_exp_f32_e32 v95, v95
	s_waitcnt lgkmcnt(1)
	v_mfma_f32_16x16x32_bf16 v[48:51], v[214:217], v[222:225], v[48:51]
	v_exp_f32_e32 v96, v96
	v_exp_f32_e32 v97, v97
	v_exp_f32_e32 v98, v98
	v_exp_f32_e32 v99, v99
	v_pk_add_f32 v[76:77], v[76:77], v[178:179] op_sel_hi:[1,0]
	v_pk_add_f32 v[78:79], v[78:79], v[178:179] op_sel_hi:[1,0]
	v_pk_add_f32 v[80:81], v[80:81], v[178:179] op_sel_hi:[1,0]
	v_pk_add_f32 v[82:83], v[82:83], v[178:179] op_sel_hi:[1,0]
	v_cvt_pk_bf16_f32 v222, v92, v93
	v_cvt_pk_bf16_f32 v223, v94, v95
	v_cvt_pk_bf16_f32 v224, v96, v97
	v_cvt_pk_bf16_f32 v225, v98, v99
	v_exp_f32_e32 v76, v76
	v_exp_f32_e32 v77, v77
	s_nop 1
	v_mfma_f32_16x16x32_bf16 v[60:63], v[198:201], v[222:225], v[60:63]
	v_exp_f32_e32 v78, v78
	v_exp_f32_e32 v79, v79
	v_mfma_f32_16x16x32_bf16 v[56:59], v[202:205], v[222:225], v[56:59]
	v_exp_f32_e32 v80, v80
	v_exp_f32_e32 v81, v81
	v_mfma_f32_16x16x32_bf16 v[52:55], v[210:213], v[222:225], v[52:55]
	v_exp_f32_e32 v82, v82
	v_exp_f32_e32 v83, v83
	s_waitcnt lgkmcnt(0)
	v_mfma_f32_16x16x32_bf16 v[48:51], v[218:221], v[222:225], v[48:51]
	ds_read_b128 v[234:237], v116 offset:2304
	ds_read_b128 v[238:241], v116
	v_pk_mul_f32 v[20:21], v[20:21], v[186:187] op_sel_hi:[1,0]
	v_pk_mul_f32 v[22:23], v[22:23], v[186:187] op_sel_hi:[1,0]
	v_pk_mul_f32 v[16:17], v[16:17], v[186:187] op_sel_hi:[1,0]
	v_pk_mul_f32 v[18:19], v[18:19], v[186:187] op_sel_hi:[1,0]
	s_nop 1
	v_mfma_f32_16x16x32_bf16 v[20:23], v[206:209], v[226:229], v[20:23]
	v_pk_add_f32 v[90:91], v[68:69], v[70:71]
	v_pk_add_f32 v[178:179], v[72:73], v[74:75]
	v_mfma_f32_16x16x32_bf16 v[16:19], v[214:217], v[226:229], v[16:19]
	v_cvt_pk_bf16_f32 v226, v76, v77
	v_cvt_pk_bf16_f32 v227, v78, v79
	v_cvt_pk_bf16_f32 v228, v80, v81
	v_cvt_pk_bf16_f32 v229, v82, v83
	v_pk_add_f32 v[90:91], v[90:91], v[64:65]
	v_pk_add_f32 v[178:179], v[178:179], v[100:101]
	s_nop 1
	v_mfma_f32_16x16x32_bf16 v[28:31], v[198:201], v[226:229], v[28:31]
	v_pk_add_f32 v[90:91], v[90:91], v[66:67]
	v_pk_add_f32 v[178:179], v[178:179], v[102:103]
	v_mfma_f32_16x16x32_bf16 v[24:27], v[202:205], v[226:229], v[24:27]
	v_pk_add_f32 v[90:91], v[90:91], v[92:93]
	v_pk_add_f32 v[178:179], v[178:179], v[76:77]
	v_mfma_f32_16x16x32_bf16 v[20:23], v[210:213], v[226:229], v[20:23]
	v_pk_add_f32 v[90:91], v[90:91], v[94:95]
	v_pk_add_f32 v[178:179], v[178:179], v[78:79]
	v_mfma_f32_16x16x32_bf16 v[16:19], v[218:221], v[226:229], v[16:19]
	v_pk_add_f32 v[90:91], v[90:91], v[96:97]
	v_pk_add_f32 v[178:179], v[178:179], v[80:81]
	v_pk_add_f32 v[90:91], v[90:91], v[98:99]
	v_pk_add_f32 v[178:179], v[178:179], v[82:83]
	v_add_f32_e32 v64, v90, v91
	v_add_f32_e32 v65, v178, v179
	v_mov_b32_e32 v66, v64
	v_mov_b32_e32 v67, v65
	s_nop 0
	v_permlane16_swap_b32_e32 v66, v64
	v_permlane16_swap_b32_e32 v67, v65
	v_pk_add_f32 v[64:65], v[64:65], v[66:67]
	s_nop 0
	v_mov_b32_e32 v66, v64
	v_mov_b32_e32 v67, v65
	s_nop 0
	v_permlane32_swap_b32_e32 v66, v64
	v_permlane32_swap_b32_e32 v67, v65
	v_pk_add_f32 v[64:65], v[64:65], v[66:67]
	s_nop 0
	v_pk_fma_f32 v[158:159], v[158:159], v[88:89], v[64:65]
	s_cmpk_lg_i32 s0, 0x80
	s_cbranch_scc1 .Lpast_qskip
	s_cmp_lg_u64 s[22:23], 0
	s_cbranch_scc1 .Lpast_qskip
	v_mov_b32_e32 v233, 0
	s_waitcnt vmcnt(1)
	v_and_b32_e32 v137, 0xfff, v141
	v_lshlrev_b32_e32 v232, 7, v137
	v_lshl_add_u64 v[4:5], v[156:157], 0, v[232:233]
	global_load_dwordx4 v[0:3], v[4:5], off
	s_nop 0
	global_load_dwordx4 v[4:7], v[4:5], off offset:64
	s_waitcnt vmcnt(2)
	v_and_b32_e32 v139, 0xfff, v149
	v_lshlrev_b32_e32 v232, 7, v139
	v_lshl_add_u64 v[12:13], v[156:157], 0, v[232:233]
	global_load_dwordx4 v[8:11], v[12:13], off
	s_nop 0
	global_load_dwordx4 v[12:15], v[12:13], off offset:64
